# grid barrier: waiters poll the cross-XCD arrival counter for >= (round+1)*nx instead of the generation word (one agent-scope round trip less on the release path)
# speedup vs baseline: 1.0046x; 1.0046x over previous
.LBB0_1911:
	s_or_b64 exec, exec, s[20:21]
	v_cvt_f32_u32_e32 v5, v3
	s_waitcnt vmcnt(0)
	v_readfirstlane_b32 s20, v4
	v_sub_u32_e32 v4, 0, v3
	v_rcp_iflag_f32_e32 v5, v5
	v_add_u32_e32 v6, s20, v0
	v_mul_f32_e32 v5, 0x4f7ffffe, v5
	v_cvt_u32_f32_e32 v5, v5
	v_mul_lo_u32 v0, v4, v5
	v_mul_hi_u32 v0, v5, v0
	v_add_u32_e32 v0, v5, v0
	v_mul_hi_u32 v0, v6, v0
	v_mul_lo_u32 v4, v0, v3
	v_sub_u32_e32 v4, v6, v4
	v_add_u32_e32 v5, 1, v0
	v_cmp_ge_u32_e32 vcc, v4, v3
	s_nop 1
	v_cndmask_b32_e32 v0, v0, v5, vcc
	v_sub_u32_e32 v5, v4, v3
	v_cndmask_b32_e32 v4, v4, v5, vcc
	v_add_u32_e32 v5, 1, v0
	v_cmp_ge_u32_e32 vcc, v4, v3
	v_add_u32_e32 v4, 1, v6
	s_nop 0
	v_cndmask_b32_e32 v0, v0, v5, vcc
	v_mul_lo_u32 v5, v3, v0
	v_add_u32_e32 v3, v5, v3
	v_cmp_ne_u32_e32 vcc, v4, v3
	s_and_saveexec_b64 s[20:21], vcc
	s_xor_b64 s[20:21], exec, s[20:21]
	s_cbranch_execz .LBB0_1925
	v_readlane_b32 s24, v250, 8
	v_readlane_b32 s25, v250, 9
	v_add_u32_e32 v17, 1, v0
	v_mul_lo_u32 v17, v17, v2
	s_waitcnt lgkmcnt(0)
	s_nop 3
	global_load_dword v2, v1, s[24:25] sc1
	s_waitcnt vmcnt(0)
	v_cmp_lt_u32_e32 vcc, v2, v17
	s_and_saveexec_b64 s[24:25], vcc
	s_cbranch_execz .LBB0_1924
	s_mov_b32 s23, 1
	s_mov_b64 s[36:37], 0
	s_branch .LBB0_1915

.LBB0_1917:
	v_readlane_b32 s30, v250, 8
	v_readlane_b32 s31, v250, 9
	s_add_i32 s23, s23, 1
	s_mov_b64 s[42:43], -1
	s_nop 2
	global_load_dword v2, v1, s[30:31] sc1
	s_waitcnt vmcnt(0)
	v_cmp_ge_u32_e32 vcc, v2, v17
	s_orn2_b64 s[40:41], vcc, exec
	s_branch .LBB0_1914

.LBB0_1928:
	s_or_b64 exec, exec, s[24:25]
	s_waitcnt vmcnt(0)
	v_readfirstlane_b32 s20, v3
	v_sub_u32_e32 v4, 0, v2
	s_mov_b64 s[24:25], -1
	v_add_u32_e32 v3, s20, v0
	v_cvt_f32_u32_e32 v0, v2
	v_readlane_b32 s20, v250, 10
	v_readlane_b32 s21, v250, 11
	v_rcp_iflag_f32_e32 v0, v0
	s_nop 0
	v_mul_f32_e32 v0, 0x4f7ffffe, v0
	v_cvt_u32_f32_e32 v0, v0
	v_mul_lo_u32 v4, v4, v0
	v_mul_hi_u32 v4, v0, v4
	v_add_u32_e32 v0, v0, v4
	v_mul_hi_u32 v0, v3, v0
	v_mul_lo_u32 v4, v0, v2
	v_sub_u32_e32 v4, v3, v4
	v_cmp_ge_u32_e32 vcc, v4, v2
	v_add_u32_e32 v5, 1, v0
	v_add_u32_e32 v3, 1, v3
	v_cndmask_b32_e32 v0, v0, v5, vcc
	v_sub_u32_e32 v5, v4, v2
	v_cndmask_b32_e32 v4, v4, v5, vcc
	v_cmp_ge_u32_e32 vcc, v4, v2
	v_add_u32_e32 v4, 1, v0
	s_nop 0
	v_cndmask_b32_e32 v0, v0, v4, vcc
	v_mul_lo_u32 v4, v2, v0
	v_add_u32_e32 v2, v4, v2
	v_mov_b32_e32 v17, v2
	v_cmp_ne_u32_e32 vcc, v3, v2
	v_mov_b64_e32 v[2:3], s[20:21]
	s_and_saveexec_b64 s[20:21], vcc
	s_cbranch_execz .LBB0_1940
	v_readlane_b32 s24, v250, 8
	v_readlane_b32 s25, v250, 9
	s_mov_b64 s[36:37], 0
	s_nop 3
	global_load_dword v2, v1, s[24:25] sc1
	s_waitcnt vmcnt(0)
	v_cmp_lt_u32_e32 vcc, v2, v17
	s_and_saveexec_b64 s[24:25], vcc
	s_cbranch_execz .LBB0_1939
	s_mov_b32 s23, 1
	s_branch .LBB0_1932
